# speedup vs baseline: 1.0347x; 1.0043x over previous
.LBB0_356:
	ds_read_b128 v[138:141], v134
	ds_read_b128 v[142:145], v134 offset:1024
	ds_read_b128 v[146:149], v134 offset:2048
	ds_read_b128 v[150:153], v134 offset:3072
	ds_read_b128 v[154:157], v187
	ds_read_b128 v[158:161], v187 offset:1024
	ds_read_b128 v[188:191], v186
	ds_read_b128 v[192:195], v186 offset:1024
	ds_read_b128 v[196:199], v185
	ds_read_b128 v[200:203], v185 offset:1024
	ds_read_b128 v[204:207], v184
	ds_read_b128 v[208:211], v184 offset:1024
	s_waitcnt lgkmcnt(8)
	s_waitcnt vmcnt(10)
	s_barrier
	s_waitcnt lgkmcnt(0)
	s_setprio 1
	s_waitcnt lgkmcnt(0)
	v_mfma_f32_16x16x32_bf16 v[124:127], v[138:141], v[154:157], v[124:127]
	v_mfma_f32_16x16x32_bf16 v[120:123], v[146:149], v[154:157], v[120:123]
	v_mfma_f32_16x16x32_bf16 v[116:119], v[138:141], v[188:191], v[116:119]
	v_mfma_f32_16x16x32_bf16 v[112:115], v[146:149], v[188:191], v[112:115]
	v_mfma_f32_16x16x32_bf16 v[108:111], v[138:141], v[196:199], v[108:111]
	v_mfma_f32_16x16x32_bf16 v[104:107], v[146:149], v[196:199], v[104:107]
	v_mfma_f32_16x16x32_bf16 v[100:103], v[138:141], v[204:207], v[100:103]
	v_mfma_f32_16x16x32_bf16 v[96:99], v[146:149], v[204:207], v[96:99]
	v_mfma_f32_16x16x32_bf16 v[124:127], v[142:145], v[158:161], v[124:127]
	v_mfma_f32_16x16x32_bf16 v[120:123], v[150:153], v[158:161], v[120:123]
	v_mfma_f32_16x16x32_bf16 v[116:119], v[142:145], v[192:195], v[116:119]
	v_mfma_f32_16x16x32_bf16 v[112:115], v[150:153], v[192:195], v[112:115]
	v_mfma_f32_16x16x32_bf16 v[108:111], v[142:145], v[200:203], v[108:111]
	v_mfma_f32_16x16x32_bf16 v[104:107], v[150:153], v[200:203], v[104:107]
	v_mfma_f32_16x16x32_bf16 v[100:103], v[142:145], v[208:211], v[100:103]
	v_mfma_f32_16x16x32_bf16 v[96:99], v[150:153], v[208:211], v[96:99]
	s_setprio 0
	s_barrier
	s_add_u32 s70, s18, 1
	s_addc_u32 s71, s19, 0
	s_lshl_b64 s[72:73], s[70:71], s22
	s_add_u32 s74, s17, s72
	s_addc_u32 s75, s29, s73
	v_lshl_add_u64 v[162:163], s[74:75], 0, v[128:129]
	v_readfirstlane_b32 s23, v182
	s_add_u32 s74, s74, s25
	s_mov_b32 m0, s23
	s_addc_u32 s75, s75, 0
	v_readfirstlane_b32 s23, v181
	ds_read_b128 v[212:215], v131
	ds_read_b128 v[216:219], v131 offset:1024
	ds_read_b128 v[220:223], v131 offset:2048
	ds_read_b128 v[224:227], v131 offset:3072
	global_load_lds_dwordx4 v[162:163], off
	v_lshl_add_u64 v[162:163], s[74:75], 0, v[128:129]
	s_mov_b32 m0, s23
	s_nop 0
	global_load_lds_dwordx4 v[162:163], off
	s_lshl_b64 s[70:71], s[70:71], s28
	s_add_u32 s74, s15, s70
	s_addc_u32 s75, s30, s71
	v_lshl_add_u64 v[162:163], s[74:75], 0, v[164:165]
	v_readfirstlane_b32 s23, v169
	s_add_u32 s74, s74, s24
	s_mov_b32 m0, s23
	s_addc_u32 s75, s75, 0
	v_readfirstlane_b32 s23, v180
	global_load_lds_dwordx4 v[162:163], off
	v_lshl_add_u64 v[162:163], s[74:75], 0, v[164:165]
	s_mov_b32 m0, s23
	s_nop 0
	global_load_lds_dwordx4 v[162:163], off
	s_waitcnt vmcnt(12)
	s_barrier
	s_waitcnt lgkmcnt(0)
	s_setprio 1
	s_waitcnt lgkmcnt(0)
	v_mfma_f32_16x16x32_bf16 v[92:95], v[212:215], v[154:157], v[92:95]
	v_mfma_f32_16x16x32_bf16 v[88:91], v[220:223], v[154:157], v[88:91]
	v_mfma_f32_16x16x32_bf16 v[84:87], v[212:215], v[188:191], v[84:87]
	v_mfma_f32_16x16x32_bf16 v[80:83], v[220:223], v[188:191], v[80:83]
	v_mfma_f32_16x16x32_bf16 v[76:79], v[212:215], v[196:199], v[76:79]
	v_mfma_f32_16x16x32_bf16 v[72:75], v[220:223], v[196:199], v[72:75]
	v_mfma_f32_16x16x32_bf16 v[68:71], v[212:215], v[204:207], v[68:71]
	v_mfma_f32_16x16x32_bf16 v[64:67], v[220:223], v[204:207], v[64:67]
	v_mfma_f32_16x16x32_bf16 v[92:95], v[216:219], v[158:161], v[92:95]
	v_mfma_f32_16x16x32_bf16 v[88:91], v[224:227], v[158:161], v[88:91]
	v_mfma_f32_16x16x32_bf16 v[84:87], v[216:219], v[192:195], v[84:87]
	v_mfma_f32_16x16x32_bf16 v[80:83], v[224:227], v[192:195], v[80:83]
	v_mfma_f32_16x16x32_bf16 v[76:79], v[216:219], v[200:203], v[76:79]
	v_mfma_f32_16x16x32_bf16 v[72:75], v[224:227], v[200:203], v[72:75]
	v_mfma_f32_16x16x32_bf16 v[68:71], v[216:219], v[208:211], v[68:71]
	v_mfma_f32_16x16x32_bf16 v[64:67], v[224:227], v[208:211], v[64:67]
	s_setprio 0
	s_barrier
	ds_read_b128 v[154:157], v187 offset:16384
	ds_read_b128 v[158:161], v187 offset:17408
	ds_read_b128 v[188:191], v186 offset:16384
	ds_read_b128 v[192:195], v186 offset:17408
	ds_read_b128 v[196:199], v185 offset:16384
	ds_read_b128 v[200:203], v185 offset:17408
	ds_read_b128 v[204:207], v184 offset:16384
	ds_read_b128 v[208:211], v184 offset:17408
	s_add_u32 s72, s20, s72
	s_addc_u32 s73, s21, s73
	v_lshl_add_u64 v[162:163], s[72:73], 0, v[128:129]
	v_readfirstlane_b32 s23, v179
	s_add_u32 s72, s72, s25
	s_mov_b32 m0, s23
	s_addc_u32 s73, s73, 0
	v_readfirstlane_b32 s23, v178
	global_load_lds_dwordx4 v[162:163], off
	v_lshl_add_u64 v[162:163], s[72:73], 0, v[128:129]
	s_mov_b32 m0, s23
	s_nop 0
	global_load_lds_dwordx4 v[162:163], off
	s_barrier
	s_waitcnt lgkmcnt(0)
	s_setprio 1
	s_waitcnt lgkmcnt(0)
	v_mfma_f32_16x16x32_bf16 v[60:63], v[138:141], v[154:157], v[60:63]
	v_mfma_f32_16x16x32_bf16 v[56:59], v[146:149], v[154:157], v[56:59]
	v_mfma_f32_16x16x32_bf16 v[52:55], v[138:141], v[188:191], v[52:55]
	v_mfma_f32_16x16x32_bf16 v[48:51], v[146:149], v[188:191], v[48:51]
	v_mfma_f32_16x16x32_bf16 v[44:47], v[138:141], v[196:199], v[44:47]
	v_mfma_f32_16x16x32_bf16 v[40:43], v[146:149], v[196:199], v[40:43]
	v_mfma_f32_16x16x32_bf16 v[36:39], v[138:141], v[204:207], v[36:39]
	v_mfma_f32_16x16x32_bf16 v[32:35], v[146:149], v[204:207], v[32:35]
	v_mfma_f32_16x16x32_bf16 v[60:63], v[142:145], v[158:161], v[60:63]
	v_mfma_f32_16x16x32_bf16 v[56:59], v[150:153], v[158:161], v[56:59]
	v_mfma_f32_16x16x32_bf16 v[52:55], v[142:145], v[192:195], v[52:55]
	v_mfma_f32_16x16x32_bf16 v[48:51], v[150:153], v[192:195], v[48:51]
	v_mfma_f32_16x16x32_bf16 v[44:47], v[142:145], v[200:203], v[44:47]
	v_mfma_f32_16x16x32_bf16 v[40:43], v[150:153], v[200:203], v[40:43]
	v_mfma_f32_16x16x32_bf16 v[36:39], v[142:145], v[208:211], v[36:39]
	v_mfma_f32_16x16x32_bf16 v[32:35], v[150:153], v[208:211], v[32:35]
	s_setprio 0
	s_barrier
	s_add_u32 s70, s26, s70
	s_addc_u32 s71, s27, s71
	v_lshl_add_u64 v[162:163], s[70:71], 0, v[164:165]
	v_readfirstlane_b32 s23, v177
	s_add_u32 s70, s70, s24
	s_mov_b32 m0, s23
	s_addc_u32 s71, s71, 0
	v_readfirstlane_b32 s23, v176
	global_load_lds_dwordx4 v[162:163], off
	v_lshl_add_u64 v[162:163], s[70:71], 0, v[164:165]
	s_mov_b32 m0, s23
	s_nop 0
	global_load_lds_dwordx4 v[162:163], off
	s_waitcnt vmcnt(12)
	s_barrier
	s_setprio 1
	v_mfma_f32_16x16x32_bf16 v[28:31], v[212:215], v[154:157], v[28:31]
	v_mfma_f32_16x16x32_bf16 v[24:27], v[220:223], v[154:157], v[24:27]
	v_mfma_f32_16x16x32_bf16 v[20:23], v[212:215], v[188:191], v[20:23]
	v_mfma_f32_16x16x32_bf16 v[16:19], v[220:223], v[188:191], v[16:19]
	v_mfma_f32_16x16x32_bf16 v[12:15], v[212:215], v[196:199], v[12:15]
	v_mfma_f32_16x16x32_bf16 v[8:11], v[220:223], v[196:199], v[8:11]
	v_mfma_f32_16x16x32_bf16 v[4:7], v[212:215], v[204:207], v[4:7]
	v_mfma_f32_16x16x32_bf16 v[0:3], v[220:223], v[204:207], v[0:3]
	v_mfma_f32_16x16x32_bf16 v[28:31], v[216:219], v[158:161], v[28:31]
	v_mfma_f32_16x16x32_bf16 v[24:27], v[224:227], v[158:161], v[24:27]
	v_mfma_f32_16x16x32_bf16 v[20:23], v[216:219], v[192:195], v[20:23]
	v_mfma_f32_16x16x32_bf16 v[16:19], v[224:227], v[192:195], v[16:19]
	v_mfma_f32_16x16x32_bf16 v[12:15], v[216:219], v[200:203], v[12:15]
	v_mfma_f32_16x16x32_bf16 v[8:11], v[224:227], v[200:203], v[8:11]
	v_mfma_f32_16x16x32_bf16 v[4:7], v[216:219], v[208:211], v[4:7]
	v_mfma_f32_16x16x32_bf16 v[0:3], v[224:227], v[208:211], v[0:3]
	s_setprio 0
	s_barrier
	ds_read_b128 v[138:141], v130
	ds_read_b128 v[142:145], v130 offset:1024
	ds_read_b128 v[146:149], v130 offset:2048
	ds_read_b128 v[150:153], v130 offset:3072
	ds_read_b128 v[154:157], v187 offset:32768
	ds_read_b128 v[158:161], v187 offset:33792
	ds_read_b128 v[188:191], v186 offset:32768
	ds_read_b128 v[192:195], v186 offset:33792
	ds_read_b128 v[196:199], v185 offset:32768
	ds_read_b128 v[200:203], v185 offset:33792
	ds_read_b128 v[204:207], v184 offset:32768
	ds_read_b128 v[208:211], v184 offset:33792
	s_waitcnt lgkmcnt(8)
	s_waitcnt vmcnt(10)
	s_barrier
	s_waitcnt lgkmcnt(0)
	s_setprio 1
	s_waitcnt lgkmcnt(0)
	v_mfma_f32_16x16x32_bf16 v[124:127], v[138:141], v[154:157], v[124:127]
	v_mfma_f32_16x16x32_bf16 v[120:123], v[146:149], v[154:157], v[120:123]
	v_mfma_f32_16x16x32_bf16 v[116:119], v[138:141], v[188:191], v[116:119]
	v_mfma_f32_16x16x32_bf16 v[112:115], v[146:149], v[188:191], v[112:115]
	v_mfma_f32_16x16x32_bf16 v[108:111], v[138:141], v[196:199], v[108:111]
	v_mfma_f32_16x16x32_bf16 v[104:107], v[146:149], v[196:199], v[104:107]
	v_mfma_f32_16x16x32_bf16 v[100:103], v[138:141], v[204:207], v[100:103]
	v_mfma_f32_16x16x32_bf16 v[96:99], v[146:149], v[204:207], v[96:99]
	v_mfma_f32_16x16x32_bf16 v[124:127], v[142:145], v[158:161], v[124:127]
	v_mfma_f32_16x16x32_bf16 v[120:123], v[150:153], v[158:161], v[120:123]
	v_mfma_f32_16x16x32_bf16 v[116:119], v[142:145], v[192:195], v[116:119]
	v_mfma_f32_16x16x32_bf16 v[112:115], v[150:153], v[192:195], v[112:115]
	v_mfma_f32_16x16x32_bf16 v[108:111], v[142:145], v[200:203], v[108:111]
	v_mfma_f32_16x16x32_bf16 v[104:107], v[150:153], v[200:203], v[104:107]
	v_mfma_f32_16x16x32_bf16 v[100:103], v[142:145], v[208:211], v[100:103]
	v_mfma_f32_16x16x32_bf16 v[96:99], v[150:153], v[208:211], v[96:99]
	s_setprio 0
	s_barrier
	s_add_u32 s18, s18, 2
	s_addc_u32 s19, s19, 0
	s_lshl_b64 s[70:71], s[18:19], s22
	s_add_u32 s72, s17, s70
	s_addc_u32 s73, s29, s71
	v_lshl_add_u64 v[162:163], s[72:73], 0, v[128:129]
	v_readfirstlane_b32 s23, v175
	s_add_u32 s72, s72, s25
	s_mov_b32 m0, s23
	s_addc_u32 s73, s73, 0
	v_readfirstlane_b32 s23, v174
	ds_read_b128 v[212:215], v136
	ds_read_b128 v[216:219], v136 offset:1024
	ds_read_b128 v[220:223], v136 offset:2048
	ds_read_b128 v[224:227], v136 offset:3072
	global_load_lds_dwordx4 v[162:163], off
	v_lshl_add_u64 v[162:163], s[72:73], 0, v[128:129]
	s_mov_b32 m0, s23
	s_nop 0
	global_load_lds_dwordx4 v[162:163], off
	s_lshl_b64 s[72:73], s[18:19], s28
	s_add_u32 s72, s15, s72
	s_addc_u32 s73, s30, s73
	v_lshl_add_u64 v[162:163], s[72:73], 0, v[164:165]
	v_readfirstlane_b32 s23, v173
	s_add_u32 s72, s72, s24
	s_mov_b32 m0, s23
	s_addc_u32 s73, s73, 0
	v_readfirstlane_b32 s23, v172
	global_load_lds_dwordx4 v[162:163], off
	v_lshl_add_u64 v[162:163], s[72:73], 0, v[164:165]
	s_mov_b32 m0, s23
	s_nop 0
	global_load_lds_dwordx4 v[162:163], off
	s_waitcnt vmcnt(12)
	s_barrier
	s_waitcnt lgkmcnt(0)
	s_setprio 1
	s_waitcnt lgkmcnt(0)
	v_mfma_f32_16x16x32_bf16 v[92:95], v[212:215], v[154:157], v[92:95]
	v_mfma_f32_16x16x32_bf16 v[88:91], v[220:223], v[154:157], v[88:91]
	v_mfma_f32_16x16x32_bf16 v[84:87], v[212:215], v[188:191], v[84:87]
	v_mfma_f32_16x16x32_bf16 v[80:83], v[220:223], v[188:191], v[80:83]
	v_mfma_f32_16x16x32_bf16 v[76:79], v[212:215], v[196:199], v[76:79]
	v_mfma_f32_16x16x32_bf16 v[72:75], v[220:223], v[196:199], v[72:75]
	v_mfma_f32_16x16x32_bf16 v[68:71], v[212:215], v[204:207], v[68:71]
	v_mfma_f32_16x16x32_bf16 v[64:67], v[220:223], v[204:207], v[64:67]
	v_mfma_f32_16x16x32_bf16 v[92:95], v[216:219], v[158:161], v[92:95]
	v_mfma_f32_16x16x32_bf16 v[88:91], v[224:227], v[158:161], v[88:91]
	v_mfma_f32_16x16x32_bf16 v[84:87], v[216:219], v[192:195], v[84:87]
	v_mfma_f32_16x16x32_bf16 v[80:83], v[224:227], v[192:195], v[80:83]
	v_mfma_f32_16x16x32_bf16 v[76:79], v[216:219], v[200:203], v[76:79]
	v_mfma_f32_16x16x32_bf16 v[72:75], v[224:227], v[200:203], v[72:75]
	v_mfma_f32_16x16x32_bf16 v[68:71], v[216:219], v[208:211], v[68:71]
	v_mfma_f32_16x16x32_bf16 v[64:67], v[224:227], v[208:211], v[64:67]
	s_setprio 0
	s_barrier
	ds_read_b128 v[154:157], v187 offset:49152
	ds_read_b128 v[158:161], v187 offset:50176
	ds_read_b128 v[188:191], v186 offset:49152
	ds_read_b128 v[192:195], v186 offset:50176
	ds_read_b128 v[196:199], v185 offset:49152
	ds_read_b128 v[200:203], v185 offset:50176
	ds_read_b128 v[204:207], v184 offset:49152
	ds_read_b128 v[208:211], v184 offset:50176
	s_add_u32 s70, s20, s70
	s_addc_u32 s71, s21, s71
	v_lshl_add_u64 v[162:163], s[70:71], 0, v[128:129]
	v_readfirstlane_b32 s23, v171
	s_add_u32 s70, s70, s25
	s_mov_b32 m0, s23
	s_addc_u32 s71, s71, 0
	v_readfirstlane_b32 s23, v170
	global_load_lds_dwordx4 v[162:163], off
	v_lshl_add_u64 v[162:163], s[70:71], 0, v[128:129]
	s_mov_b32 m0, s23
	s_nop 0
	global_load_lds_dwordx4 v[162:163], off
	s_barrier
	s_waitcnt lgkmcnt(0)
	s_setprio 1
	s_waitcnt lgkmcnt(0)
	v_mfma_f32_16x16x32_bf16 v[60:63], v[138:141], v[154:157], v[60:63]
	v_mfma_f32_16x16x32_bf16 v[56:59], v[146:149], v[154:157], v[56:59]
	v_mfma_f32_16x16x32_bf16 v[52:55], v[138:141], v[188:191], v[52:55]
	v_mfma_f32_16x16x32_bf16 v[48:51], v[146:149], v[188:191], v[48:51]
	v_mfma_f32_16x16x32_bf16 v[44:47], v[138:141], v[196:199], v[44:47]
	v_mfma_f32_16x16x32_bf16 v[40:43], v[146:149], v[196:199], v[40:43]
	v_mfma_f32_16x16x32_bf16 v[36:39], v[138:141], v[204:207], v[36:39]
	v_mfma_f32_16x16x32_bf16 v[32:35], v[146:149], v[204:207], v[32:35]
	v_mfma_f32_16x16x32_bf16 v[60:63], v[142:145], v[158:161], v[60:63]
	v_mfma_f32_16x16x32_bf16 v[56:59], v[150:153], v[158:161], v[56:59]
	v_mfma_f32_16x16x32_bf16 v[52:55], v[142:145], v[192:195], v[52:55]
	v_mfma_f32_16x16x32_bf16 v[48:51], v[150:153], v[192:195], v[48:51]
	v_mfma_f32_16x16x32_bf16 v[44:47], v[142:145], v[200:203], v[44:47]
	v_mfma_f32_16x16x32_bf16 v[40:43], v[150:153], v[200:203], v[40:43]
	v_mfma_f32_16x16x32_bf16 v[36:39], v[142:145], v[208:211], v[36:39]
	v_mfma_f32_16x16x32_bf16 v[32:35], v[150:153], v[208:211], v[32:35]
	s_setprio 0
	s_barrier
	s_lshl_b64 s[70:71], s[18:19], s28
	s_add_u32 s70, s26, s70
	s_addc_u32 s71, s27, s71
	v_lshl_add_u64 v[162:163], s[70:71], 0, v[164:165]
	v_readfirstlane_b32 s23, v133
	s_add_u32 s70, s70, s24
	s_mov_b32 m0, s23
	s_addc_u32 s71, s71, 0
	v_readfirstlane_b32 s23, v132
	global_load_lds_dwordx4 v[162:163], off
	v_lshl_add_u64 v[162:163], s[70:71], 0, v[164:165]
	s_mov_b32 m0, s23
	s_nop 0
	global_load_lds_dwordx4 v[162:163], off
	s_waitcnt vmcnt(12)
	s_barrier
	s_setprio 1
	v_mfma_f32_16x16x32_bf16 v[28:31], v[212:215], v[154:157], v[28:31]
	v_mfma_f32_16x16x32_bf16 v[24:27], v[220:223], v[154:157], v[24:27]
	v_mfma_f32_16x16x32_bf16 v[20:23], v[212:215], v[188:191], v[20:23]
	v_mfma_f32_16x16x32_bf16 v[16:19], v[220:223], v[188:191], v[16:19]
	v_mfma_f32_16x16x32_bf16 v[12:15], v[212:215], v[196:199], v[12:15]
	v_mfma_f32_16x16x32_bf16 v[8:11], v[220:223], v[196:199], v[8:11]
	v_mfma_f32_16x16x32_bf16 v[4:7], v[212:215], v[204:207], v[4:7]
	v_mfma_f32_16x16x32_bf16 v[0:3], v[220:223], v[204:207], v[0:3]
	v_mfma_f32_16x16x32_bf16 v[28:31], v[216:219], v[158:161], v[28:31]
	v_mfma_f32_16x16x32_bf16 v[24:27], v[224:227], v[158:161], v[24:27]
	v_mfma_f32_16x16x32_bf16 v[20:23], v[216:219], v[192:195], v[20:23]
	v_mfma_f32_16x16x32_bf16 v[16:19], v[224:227], v[192:195], v[16:19]
	v_mfma_f32_16x16x32_bf16 v[12:15], v[216:219], v[200:203], v[12:15]
	v_mfma_f32_16x16x32_bf16 v[8:11], v[224:227], v[200:203], v[8:11]
	v_mfma_f32_16x16x32_bf16 v[4:7], v[216:219], v[208:211], v[4:7]
	v_mfma_f32_16x16x32_bf16 v[0:3], v[224:227], v[208:211], v[0:3]
	s_setprio 0
	s_add_i32 s23, s18, -3
	s_cmp_lt_u32 s23, 28
	s_barrier
	s_cbranch_scc1 .LBB0_356
	s_lshl_b64 s[18:19], 31, s28
	s_add_u32 s18, s26, s18
	s_addc_u32 s19, s27, s19
	v_lshl_add_u64 v[128:129], s[18:19], 0, v[164:165]
	v_readfirstlane_b32 s15, v133
	s_add_u32 s18, s18, s24
	s_mov_b32 m0, s15
	s_addc_u32 s19, s19, 0
	v_readfirstlane_b32 s15, v132
	ds_read_b128 v[138:141], v134
	ds_read_b128 v[142:145], v134 offset:1024
	ds_read_b128 v[146:149], v134 offset:2048
	ds_read_b128 v[150:153], v134 offset:3072
	ds_read_b128 v[154:157], v187
	ds_read_b128 v[158:161], v187 offset:1024
	ds_read_b128 v[188:191], v186
	ds_read_b128 v[192:195], v186 offset:1024
	ds_read_b128 v[196:199], v185
	ds_read_b128 v[200:203], v185 offset:1024
	ds_read_b128 v[204:207], v184
	ds_read_b128 v[208:211], v184 offset:1024
	global_load_lds_dwordx4 v[128:129], off
	v_lshl_add_u64 v[128:129], s[18:19], 0, v[164:165]
	s_mov_b32 m0, s15
	s_nop 0
	global_load_lds_dwordx4 v[128:129], off
	s_waitcnt vmcnt(10)
	s_barrier
	s_waitcnt lgkmcnt(0)
	s_setprio 1
	s_waitcnt lgkmcnt(0)
	v_mfma_f32_16x16x32_bf16 v[124:127], v[138:141], v[154:157], v[124:127]
	v_mfma_f32_16x16x32_bf16 v[120:123], v[146:149], v[154:157], v[120:123]
	v_mfma_f32_16x16x32_bf16 v[116:119], v[138:141], v[188:191], v[116:119]
	v_mfma_f32_16x16x32_bf16 v[112:115], v[146:149], v[188:191], v[112:115]
	v_mfma_f32_16x16x32_bf16 v[108:111], v[138:141], v[196:199], v[108:111]
	v_mfma_f32_16x16x32_bf16 v[104:107], v[146:149], v[196:199], v[104:107]
	v_mfma_f32_16x16x32_bf16 v[100:103], v[138:141], v[204:207], v[100:103]
	v_mfma_f32_16x16x32_bf16 v[96:99], v[146:149], v[204:207], v[96:99]
	v_mfma_f32_16x16x32_bf16 v[124:127], v[142:145], v[158:161], v[124:127]
	v_mfma_f32_16x16x32_bf16 v[120:123], v[150:153], v[158:161], v[120:123]
	v_mfma_f32_16x16x32_bf16 v[116:119], v[142:145], v[192:195], v[116:119]
	v_mfma_f32_16x16x32_bf16 v[112:115], v[150:153], v[192:195], v[112:115]
	v_mfma_f32_16x16x32_bf16 v[108:111], v[142:145], v[200:203], v[108:111]
	v_mfma_f32_16x16x32_bf16 v[104:107], v[150:153], v[200:203], v[104:107]
	v_mfma_f32_16x16x32_bf16 v[100:103], v[142:145], v[208:211], v[100:103]
	v_mfma_f32_16x16x32_bf16 v[96:99], v[150:153], v[208:211], v[96:99]
	s_setprio 0
	s_barrier
	ds_read_b128 v[132:135], v131
	ds_read_b128 v[212:215], v131 offset:1024
	ds_read_b128 v[216:219], v131 offset:2048
	ds_read_b128 v[220:223], v131 offset:3072
	s_barrier
	s_waitcnt lgkmcnt(0)
	s_setprio 1
	s_waitcnt lgkmcnt(0)
	v_mfma_f32_16x16x32_bf16 v[92:95], v[132:135], v[154:157], v[92:95]
	v_mfma_f32_16x16x32_bf16 v[88:91], v[216:219], v[154:157], v[88:91]
	v_mfma_f32_16x16x32_bf16 v[84:87], v[132:135], v[188:191], v[84:87]
	v_mfma_f32_16x16x32_bf16 v[80:83], v[216:219], v[188:191], v[80:83]
	v_mfma_f32_16x16x32_bf16 v[76:79], v[132:135], v[196:199], v[76:79]
	v_mfma_f32_16x16x32_bf16 v[72:75], v[216:219], v[196:199], v[72:75]
	v_mfma_f32_16x16x32_bf16 v[68:71], v[132:135], v[204:207], v[68:71]
	v_mfma_f32_16x16x32_bf16 v[64:67], v[216:219], v[204:207], v[64:67]
	v_mfma_f32_16x16x32_bf16 v[154:157], v[212:215], v[158:161], v[92:95]
	v_mfma_f32_16x16x32_bf16 v[158:161], v[220:223], v[158:161], v[88:91]
	v_mfma_f32_16x16x32_bf16 v[188:191], v[212:215], v[192:195], v[84:87]
	v_mfma_f32_16x16x32_bf16 v[192:195], v[220:223], v[192:195], v[80:83]
	v_mfma_f32_16x16x32_bf16 v[196:199], v[212:215], v[200:203], v[76:79]
	v_mfma_f32_16x16x32_bf16 v[200:203], v[220:223], v[200:203], v[72:75]
	v_mfma_f32_16x16x32_bf16 v[204:207], v[212:215], v[208:211], v[68:71]
	v_mfma_f32_16x16x32_bf16 v[208:211], v[220:223], v[208:211], v[64:67]
	s_setprio 0
	s_barrier
	s_nop 0
	ds_read_b128 v[64:67], v187 offset:16384
	ds_read_b128 v[68:71], v187 offset:17408
	ds_read_b128 v[72:75], v186 offset:16384
	ds_read_b128 v[76:79], v186 offset:17408
	ds_read_b128 v[80:83], v185 offset:16384
	ds_read_b128 v[84:87], v185 offset:17408
	ds_read_b128 v[88:91], v184 offset:16384
	ds_read_b128 v[92:95], v184 offset:17408
	s_waitcnt vmcnt(4)
	s_barrier
	s_waitcnt lgkmcnt(0)
	s_setprio 1
	s_waitcnt lgkmcnt(0)
	v_mfma_f32_16x16x32_bf16 v[60:63], v[138:141], v[64:67], v[60:63]
	v_mfma_f32_16x16x32_bf16 v[56:59], v[146:149], v[64:67], v[56:59]
	v_mfma_f32_16x16x32_bf16 v[52:55], v[138:141], v[72:75], v[52:55]
	v_mfma_f32_16x16x32_bf16 v[48:51], v[146:149], v[72:75], v[48:51]
	v_mfma_f32_16x16x32_bf16 v[224:227], v[138:141], v[80:83], v[44:47]
	v_mfma_f32_16x16x32_bf16 v[228:231], v[146:149], v[80:83], v[40:43]
	v_mfma_f32_16x16x32_bf16 v[138:141], v[138:141], v[88:91], v[36:39]
	v_mfma_f32_16x16x32_bf16 v[146:149], v[146:149], v[88:91], v[32:35]
	v_mfma_f32_16x16x32_bf16 v[32:35], v[142:145], v[68:71], v[60:63]
	v_mfma_f32_16x16x32_bf16 v[36:39], v[150:153], v[68:71], v[56:59]
	v_mfma_f32_16x16x32_bf16 v[40:43], v[142:145], v[76:79], v[52:55]
	v_mfma_f32_16x16x32_bf16 v[44:47], v[150:153], v[76:79], v[48:51]
	v_mfma_f32_16x16x32_bf16 v[48:51], v[142:145], v[84:87], v[224:227]
	v_mfma_f32_16x16x32_bf16 v[52:55], v[150:153], v[84:87], v[228:231]
	v_mfma_f32_16x16x32_bf16 v[56:59], v[142:145], v[92:95], v[138:141]
	v_mfma_f32_16x16x32_bf16 v[60:63], v[150:153], v[92:95], v[146:149]
	s_setprio 0
	s_setprio 1
	v_mfma_f32_16x16x32_bf16 v[28:31], v[132:135], v[64:67], v[28:31]
	v_mfma_f32_16x16x32_bf16 v[24:27], v[216:219], v[64:67], v[24:27]
	v_mfma_f32_16x16x32_bf16 v[20:23], v[132:135], v[72:75], v[20:23]
	v_mfma_f32_16x16x32_bf16 v[16:19], v[216:219], v[72:75], v[16:19]
	v_mfma_f32_16x16x32_bf16 v[64:67], v[132:135], v[80:83], v[12:15]
	v_mfma_f32_16x16x32_bf16 v[8:11], v[216:219], v[80:83], v[8:11]
	v_mfma_f32_16x16x32_bf16 v[72:75], v[132:135], v[88:91], v[4:7]
	v_mfma_f32_16x16x32_bf16 v[0:3], v[216:219], v[88:91], v[0:3]
	v_mfma_f32_16x16x32_bf16 v[4:7], v[212:215], v[68:71], v[28:31]
	v_mfma_f32_16x16x32_bf16 v[12:15], v[220:223], v[68:71], v[24:27]
	v_mfma_f32_16x16x32_bf16 v[20:23], v[212:215], v[76:79], v[20:23]
	v_mfma_f32_16x16x32_bf16 v[28:31], v[220:223], v[76:79], v[16:19]
	v_mfma_f32_16x16x32_bf16 v[64:67], v[212:215], v[84:87], v[64:67]
	v_mfma_f32_16x16x32_bf16 v[68:71], v[220:223], v[84:87], v[8:11]
	v_mfma_f32_16x16x32_bf16 v[72:75], v[212:215], v[92:95], v[72:75]
	v_mfma_f32_16x16x32_bf16 v[76:79], v[220:223], v[92:95], v[0:3]
	s_setprio 0
	s_barrier
	ds_read_b128 v[8:11], v130
	ds_read_b128 v[0:3], v130 offset:1024
	ds_read_b128 v[16:19], v130 offset:2048
	ds_read_b128 v[80:83], v130 offset:3072
	ds_read_b128 v[138:141], v187 offset:32768
	ds_read_b128 v[212:215], v187 offset:33792
	ds_read_b128 v[216:219], v186 offset:32768
	ds_read_b128 v[220:223], v186 offset:33792
	ds_read_b128 v[224:227], v185 offset:32768
	ds_read_b128 v[228:231], v185 offset:33792
	ds_read_b128 v[232:235], v184 offset:32768
	ds_read_b128 v[236:239], v184 offset:33792
	s_waitcnt vmcnt(2)
	s_barrier
	s_waitcnt lgkmcnt(0)
	s_setprio 1
	s_waitcnt lgkmcnt(0)
	v_mfma_f32_16x16x32_bf16 v[24:27], v[8:11], v[138:141], v[124:127]
	v_mfma_f32_16x16x32_bf16 v[84:87], v[16:19], v[138:141], v[120:123]
	v_mfma_f32_16x16x32_bf16 v[88:91], v[8:11], v[216:219], v[116:119]
	v_mfma_f32_16x16x32_bf16 v[92:95], v[16:19], v[216:219], v[112:115]
	v_mfma_f32_16x16x32_bf16 v[108:111], v[8:11], v[224:227], v[108:111]
	v_mfma_f32_16x16x32_bf16 v[104:107], v[16:19], v[224:227], v[104:107]
	v_mfma_f32_16x16x32_bf16 v[100:103], v[8:11], v[232:235], v[100:103]
	v_mfma_f32_16x16x32_bf16 v[96:99], v[16:19], v[232:235], v[96:99]
	v_mfma_f32_16x16x32_bf16 v[148:151], v[0:3], v[212:215], v[24:27]
	v_mfma_f32_16x16x32_bf16 v[144:147], v[80:83], v[212:215], v[84:87]
	v_mfma_f32_16x16x32_bf16 v[132:135], v[0:3], v[220:223], v[88:91]
	v_mfma_f32_16x16x32_bf16 v[128:131], v[80:83], v[220:223], v[92:95]
	v_mfma_f32_16x16x32_bf16 v[116:119], v[0:3], v[228:231], v[108:111]
	v_mfma_f32_16x16x32_bf16 v[112:115], v[80:83], v[228:231], v[104:107]
	v_mfma_f32_16x16x32_bf16 v[100:103], v[0:3], v[236:239], v[100:103]
	v_mfma_f32_16x16x32_bf16 v[24:27], v[80:83], v[236:239], v[96:99]
	s_setprio 0
	s_barrier
	ds_read_b128 v[92:95], v136
	ds_read_b128 v[84:87], v136 offset:1024
	ds_read_b128 v[96:99], v136 offset:2048
	ds_read_b128 v[88:91], v136 offset:3072
	s_waitcnt vmcnt(0)
	s_barrier
	s_waitcnt lgkmcnt(0)
	s_setprio 1
	s_waitcnt lgkmcnt(0)
	v_mfma_f32_16x16x32_bf16 v[104:107], v[92:95], v[138:141], v[154:157]
	v_mfma_f32_16x16x32_bf16 v[108:111], v[96:99], v[138:141], v[158:161]
	v_mfma_f32_16x16x32_bf16 v[120:123], v[92:95], v[216:219], v[188:191]
	v_mfma_f32_16x16x32_bf16 v[124:127], v[96:99], v[216:219], v[192:195]
	v_mfma_f32_16x16x32_bf16 v[160:163], v[92:95], v[224:227], v[196:199]
	v_mfma_f32_16x16x32_bf16 v[188:191], v[96:99], v[224:227], v[200:203]
	v_mfma_f32_16x16x32_bf16 v[192:195], v[92:95], v[232:235], v[204:207]
	v_mfma_f32_16x16x32_bf16 v[196:199], v[96:99], v[232:235], v[208:211]
	v_mfma_f32_16x16x32_bf16 v[156:159], v[84:87], v[212:215], v[104:107]
	v_mfma_f32_16x16x32_bf16 v[152:155], v[88:91], v[212:215], v[108:111]
	v_mfma_f32_16x16x32_bf16 v[140:143], v[84:87], v[220:223], v[120:123]
	v_mfma_f32_16x16x32_bf16 v[136:139], v[88:91], v[220:223], v[124:127]
	v_mfma_f32_16x16x32_bf16 v[124:127], v[84:87], v[228:231], v[160:163]
	v_mfma_f32_16x16x32_bf16 v[120:123], v[88:91], v[228:231], v[188:191]
	v_mfma_f32_16x16x32_bf16 v[108:111], v[84:87], v[236:239], v[192:195]
	v_mfma_f32_16x16x32_bf16 v[104:107], v[88:91], v[236:239], v[196:199]
	s_setprio 0
	s_barrier
	v_mbcnt_lo_u32_b32 v164, -1, 0
	v_mbcnt_hi_u32_b32 v164, -1, v164
	s_cmp_lt_i32 s64, 3
	v_add_u32_e32 v160, s34, v164
	v_ashrrev_i32_e32 v192, 6, v160
	v_bfe_u32 v190, v160, 8, 1
	v_and_b32_e32 v191, 3, v192
	v_and_b32_e32 v188, 15, v164
	v_bfe_u32 v189, v160, 4, 2
	s_mov_b64 s[18:19], 0
	s_cbranch_scc1 .LBB0_362
	v_lshrrev_b32_e32 v160, 4, v160
	v_lshlrev_b32_e32 v162, 9, v189
	v_lshlrev_b32_e32 v163, 9, v160
	s_mov_b64 s[20:21], -1
	s_cmp_gt_i32 s64, 3
	v_lshlrev_b32_e32 v161, 4, v188
	v_and_b32_e32 v160, 0x400, v162
	v_and_b32_e32 v162, 0x200, v163
	s_cbranch_scc0 .LBB0_360
	s_lshl_b32 s15, s66, 20
	s_lshl_b32 s20, s66, 16
	s_and_b32 s15, s15, 0xff000000
	s_and_b32 s20, s20, 0xf0000
	s_lshl_b32 s17, s68, 21
	s_or_b32 s15, s20, s15
	v_lshlrev_b32_e32 v163, 14, v191
	s_add_i32 s15, s15, s17
	v_lshlrev_b32_e32 v166, 12, v190
	v_or3_b32 v163, s15, v161, v163
	v_or3_b32 v163, v163, v166, v162
	v_add_u32_e32 v166, v163, v160
	s_mov_b64 s[20:21], 0
